# attention tile loop: stage counters rotated with moves; single post-barrier check; shared K and V DMA guards; flag mask recomputed only in the rare tail
# speedup vs baseline: 1.0303x; 1.0061x over previous
.LBB0_164:
	s_add_i32 s22, s23, -1
	s_cmp_lt_u32 s22, s16
	s_cselect_b64 s[88:89], -1, 0
	s_waitcnt vmcnt(2)
.LBB0_168:
	s_lshl_b32 s101, s33, 14
	v_add_u32_e32 v82, s101, v239
	v_add_u32_e32 v102, s101, v240
	ds_read_b128 v[98:101], v82
	ds_read_b128 v[114:117], v82 offset:8192
	ds_read_b128 v[118:121], v102
	s_barrier
.LBB0_174:
	s_lshl_b32 s22, s49, 14
	s_add_i32 s54, s22, 0
	s_cmp_ge_u32 s23, s19
	v_add_u32_e32 v249, s54, v244
	v_add_u32_e32 v212, s54, v245
	s_cbranch_scc1 .Lslow_u1e

.LBB0_188:
	v_mfma_f32_32x32x16_bf16 v[34:49], v[126:129], v[162:165], v[34:49]
	ds_read_b128 v[126:129], v212 offset:49152
	s_nop 0
	v_exp_f32_e32 v130, v82
	v_exp_f32_e32 v131, v83
	v_add_f32_e32 v132, v1, v130
	v_add_f32_e32 v133, v1, v131
	v_cvt_pk_bf16_f32 v166, v130, v131
	s_waitcnt lgkmcnt(3)
	v_mfma_f32_32x32x16_bf16 v[50:65], v[122:125], v[162:165], v[50:65]
	ds_read_b128 v[122:125], v212 offset:53248
	v_exp_f32_e32 v134, v84
	v_exp_f32_e32 v135, v85
	s_add_i32 s22, s23, 2
	v_add_f32_e32 v130, v132, v134
	v_add_f32_e32 v131, v133, v135
	v_cvt_pk_bf16_f32 v167, v134, v135
	s_mov_b32 m0, s100
	s_cmp_ge_u32 s22, s17
	s_cbranch_scc1 .LBB0_190
	global_load_lds_dwordx4 v214, s[80:81]
	s_add_i32 m0, s100, 0x2000
	s_nop 0
	global_load_lds_dwordx4 v214, s[62:63]
.LBB0_190:
	s_waitcnt lgkmcnt(2)
	v_mfma_f32_32x32x16_bf16 v[18:33], v[118:121], v[162:165], v[18:33]
	ds_read_b128 v[118:121], v212 offset:57344
	v_exp_f32_e32 v132, v86
	v_exp_f32_e32 v133, v87
	v_add_f32_e32 v130, v130, v132
	v_add_f32_e32 v131, v131, v133
	v_cvt_pk_bf16_f32 v168, v132, v133
	v_mfma_f32_32x32x16_bf16 v[2:17], v[114:117], v[162:165], v[2:17]
	ds_read_b128 v[114:117], v212 offset:61440
	v_exp_f32_e32 v132, v88
	v_exp_f32_e32 v133, v89
	v_add_f32_e32 v134, v130, v132
	v_add_f32_e32 v131, v131, v133
	v_cvt_pk_bf16_f32 v169, v132, v133
	s_waitcnt lgkmcnt(2)
	v_mfma_f32_32x32x16_bf16 v[34:49], v[126:129], v[170:173], v[34:49]
	v_add_u32_e32 v130, s54, v246
	ds_read_b128 v[126:129], v130 offset:49152
	v_exp_f32_e32 v132, v90
	v_exp_f32_e32 v133, v91
	v_add_f32_e32 v134, v134, v132
	v_add_f32_e32 v135, v131, v133
	v_cvt_pk_bf16_f32 v174, v132, v133
	v_mfma_f32_32x32x16_bf16 v[50:65], v[122:125], v[170:173], v[50:65]
	ds_read_b128 v[122:125], v130 offset:53248
	v_exp_f32_e32 v133, v92
	v_exp_f32_e32 v136, v93
	v_add_f32_e32 v131, v134, v133
	v_add_f32_e32 v132, v135, v136
	v_cvt_pk_bf16_f32 v175, v133, v136
.LBB0_192:
	s_waitcnt lgkmcnt(2)
	v_mfma_f32_32x32x16_bf16 v[18:33], v[118:121], v[170:173], v[18:33]
	ds_read_b128 v[118:121], v130 offset:57344
	v_exp_f32_e32 v133, v94
	v_exp_f32_e32 v134, v95
	v_add_f32_e32 v131, v131, v133
	v_add_f32_e32 v132, v132, v134
	v_cvt_pk_bf16_f32 v176, v133, v134
	v_mfma_f32_32x32x16_bf16 v[2:17], v[114:117], v[170:173], v[2:17]
	ds_read_b128 v[114:117], v130 offset:61440
	v_exp_f32_e32 v130, v96
	v_exp_f32_e32 v133, v97
	v_add_f32_e32 v131, v131, v130
	v_add_f32_e32 v132, v132, v133
	v_cvt_pk_bf16_f32 v177, v130, v133
	s_waitcnt lgkmcnt(2)
	v_mfma_f32_32x32x16_bf16 v[34:49], v[126:129], v[178:181], v[34:49]
	v_add_u32_e32 v130, s54, v247
	ds_read_b128 v[126:129], v130 offset:49152
	v_exp_f32_e32 v133, v98
	v_exp_f32_e32 v134, v99
	v_add_f32_e32 v131, v131, v133
	v_add_f32_e32 v132, v132, v134
	v_cvt_pk_bf16_f32 v182, v133, v134
	v_mfma_f32_32x32x16_bf16 v[50:65], v[122:125], v[178:181], v[50:65]
	v_exp_f32_e32 v133, v100
	v_exp_f32_e32 v134, v101
	ds_read_b128 v[122:125], v130 offset:53248
	v_add_f32_e32 v131, v131, v133
	v_add_f32_e32 v132, v132, v134
	v_cvt_pk_bf16_f32 v183, v133, v134
	s_add_i32 m0, s101, 0xc000
	s_cmp_eq_u64 s[88:89], 0
	s_cbranch_scc1 .LBB0_194
	global_load_lds_dwordx4 v216, s[96:97]
	s_add_i32 m0, s101, 0xe000
	s_nop 0
	global_load_lds_dwordx4 v216, s[58:59]
.LBB0_194:
	s_waitcnt lgkmcnt(2)
	v_mfma_f32_32x32x16_bf16 v[18:33], v[118:121], v[178:181], v[18:33]
	ds_read_b128 v[118:121], v130 offset:57344
	v_exp_f32_e32 v133, v102
	v_exp_f32_e32 v134, v103
	v_add_f32_e32 v131, v131, v133
	v_add_f32_e32 v132, v132, v134
	v_cvt_pk_bf16_f32 v184, v133, v134
	v_mfma_f32_32x32x16_bf16 v[2:17], v[114:117], v[178:181], v[2:17]
	ds_read_b128 v[114:117], v130 offset:61440
	v_exp_f32_e32 v130, v104
	v_exp_f32_e32 v133, v105
	v_add_f32_e32 v131, v131, v130
	v_add_f32_e32 v132, v132, v133
	v_cvt_pk_bf16_f32 v185, v130, v133
	s_waitcnt lgkmcnt(2)
	v_mfma_f32_32x32x16_bf16 v[34:49], v[126:129], v[186:189], v[34:49]
	v_exp_f32_e32 v126, v106
	v_exp_f32_e32 v127, v107
	v_add_f32_e32 v128, v131, v126
	v_add_f32_e32 v129, v132, v127
	v_cvt_pk_bf16_f32 v190, v126, v127
	v_mfma_f32_32x32x16_bf16 v[50:65], v[122:125], v[186:189], v[50:65]
	v_exp_f32_e32 v124, v108
	v_exp_f32_e32 v125, v109
	v_add_f32_e32 v122, v128, v124
	v_add_f32_e32 v123, v129, v125
	v_cvt_pk_bf16_f32 v191, v124, v125

.LBB0_200:
	s_cmp_lt_u32 s22, s17
	s_cselect_b64 s[88:89], -1, 0
	s_cbranch_scc0 .Lotail_u1o

.LBB0_208:
	s_mov_b32 s26, s33
	s_mov_b32 s33, s31
	s_mov_b32 s31, s48
	s_mov_b32 s48, s26
	s_mov_b32 s49, s26
	s_lshl_b32 s101, s33, 14
	v_add_u32_e32 v82, s101, v239
	v_add_u32_e32 v102, s101, v240
	ds_read_b128 v[98:101], v82
	ds_read_b128 v[114:117], v82 offset:8192
	ds_read_b128 v[118:121], v102
	s_barrier

.LBB0_228:
	v_mfma_f32_32x32x16_bf16 v[34:49], v[126:129], v[166:169], v[34:49]
	ds_read_b128 v[126:129], v212 offset:49152
	s_nop 0
	v_exp_f32_e32 v130, v82
	v_exp_f32_e32 v131, v83
	v_add_f32_e32 v132, v1, v130
	v_add_f32_e32 v133, v1, v131
	v_cvt_pk_bf16_f32 v162, v130, v131
	s_waitcnt lgkmcnt(3)
	v_mfma_f32_32x32x16_bf16 v[50:65], v[122:125], v[166:169], v[50:65]
	ds_read_b128 v[122:125], v212 offset:53248
	v_exp_f32_e32 v130, v84
	v_exp_f32_e32 v131, v85
	s_add_i32 s23, s23, 3
	v_add_f32_e32 v132, v132, v130
	v_add_f32_e32 v133, v133, v131
	v_cvt_pk_bf16_f32 v163, v130, v131
	s_mov_b32 m0, s100
	s_cmp_gt_u32 s23, s16
	s_cbranch_scc1 .LBB0_230
	global_load_lds_dwordx4 v214, s[50:51]
	s_add_i32 m0, s100, 0x2000
	s_nop 0
	global_load_lds_dwordx4 v214, s[4:5]
.LBB0_230:
	s_waitcnt lgkmcnt(2)
	v_mfma_f32_32x32x16_bf16 v[18:33], v[118:121], v[166:169], v[18:33]
	ds_read_b128 v[118:121], v212 offset:57344
	v_exp_f32_e32 v134, v86
	v_exp_f32_e32 v135, v87
	v_add_f32_e32 v132, v132, v134
	v_add_f32_e32 v133, v133, v135
	v_cvt_pk_bf16_f32 v164, v134, v135
	v_mfma_f32_32x32x16_bf16 v[2:17], v[114:117], v[166:169], v[2:17]
	ds_read_b128 v[114:117], v212 offset:61440
	v_exp_f32_e32 v134, v88
	v_exp_f32_e32 v135, v89
	v_add_f32_e32 v136, v132, v134
	v_add_f32_e32 v133, v133, v135
	v_cvt_pk_bf16_f32 v165, v134, v135
	s_waitcnt lgkmcnt(2)
	v_mfma_f32_32x32x16_bf16 v[34:49], v[126:129], v[174:177], v[34:49]
	v_add_u32_e32 v132, s54, v246
	ds_read_b128 v[126:129], v132 offset:49152
	v_exp_f32_e32 v134, v90
	v_exp_f32_e32 v135, v91
	v_add_f32_e32 v136, v136, v134
	v_add_f32_e32 v137, v133, v135
	v_cvt_pk_bf16_f32 v170, v134, v135
	v_mfma_f32_32x32x16_bf16 v[50:65], v[122:125], v[174:177], v[50:65]
	ds_read_b128 v[122:125], v132 offset:53248
	v_exp_f32_e32 v135, v92
	v_exp_f32_e32 v138, v93
	v_add_f32_e32 v133, v136, v135
	v_add_f32_e32 v134, v137, v138
	v_cvt_pk_bf16_f32 v171, v135, v138
.LBB0_232:
	s_waitcnt lgkmcnt(2)
	v_mfma_f32_32x32x16_bf16 v[18:33], v[118:121], v[174:177], v[18:33]
	ds_read_b128 v[118:121], v132 offset:57344
	v_exp_f32_e32 v130, v94
	v_exp_f32_e32 v131, v95
	v_add_f32_e32 v133, v133, v130
	v_add_f32_e32 v134, v134, v131
	v_cvt_pk_bf16_f32 v172, v130, v131
	v_mfma_f32_32x32x16_bf16 v[2:17], v[114:117], v[174:177], v[2:17]
	ds_read_b128 v[114:117], v132 offset:61440
	v_exp_f32_e32 v130, v96
	v_exp_f32_e32 v131, v97
	v_add_f32_e32 v133, v133, v130
	v_add_f32_e32 v134, v134, v131
	v_cvt_pk_bf16_f32 v173, v130, v131
	s_waitcnt lgkmcnt(2)
	v_mfma_f32_32x32x16_bf16 v[34:49], v[126:129], v[182:185], v[34:49]
	v_add_u32_e32 v132, s54, v247
	ds_read_b128 v[126:129], v132 offset:49152
	v_exp_f32_e32 v130, v98
	v_exp_f32_e32 v131, v99
	v_add_f32_e32 v133, v133, v130
	v_add_f32_e32 v134, v134, v131
	v_cvt_pk_bf16_f32 v178, v130, v131
	v_mfma_f32_32x32x16_bf16 v[50:65], v[122:125], v[182:185], v[50:65]
	v_exp_f32_e32 v130, v100
	v_exp_f32_e32 v131, v101
	ds_read_b128 v[122:125], v132 offset:53248
	v_add_f32_e32 v133, v133, v130
	v_add_f32_e32 v134, v134, v131
	v_cvt_pk_bf16_f32 v179, v130, v131
	s_add_i32 m0, s101, 0xc000
	s_cmp_eq_u64 s[88:89], 0
	s_cbranch_scc1 .LBB0_234
	global_load_lds_dwordx4 v216, s[0:1]
	s_add_i32 m0, s101, 0xe000
	s_nop 0
	global_load_lds_dwordx4 v216, s[52:53]
.LBB0_234:
	s_waitcnt lgkmcnt(2)
	v_mfma_f32_32x32x16_bf16 v[18:33], v[118:121], v[182:185], v[18:33]
	ds_read_b128 v[118:121], v132 offset:57344
	v_exp_f32_e32 v135, v102
	v_exp_f32_e32 v136, v103
	v_add_f32_e32 v133, v133, v135
	v_add_f32_e32 v134, v134, v136
	v_cvt_pk_bf16_f32 v180, v135, v136
	v_mfma_f32_32x32x16_bf16 v[2:17], v[114:117], v[182:185], v[2:17]
	ds_read_b128 v[114:117], v132 offset:61440
	v_exp_f32_e32 v132, v104
	v_exp_f32_e32 v135, v105
	v_add_f32_e32 v133, v133, v132
	v_add_f32_e32 v134, v134, v135
	v_cvt_pk_bf16_f32 v181, v132, v135
	s_waitcnt lgkmcnt(2)
	v_mfma_f32_32x32x16_bf16 v[34:49], v[126:129], v[190:193], v[34:49]
	v_exp_f32_e32 v126, v106
	v_exp_f32_e32 v127, v107
	v_add_f32_e32 v128, v133, v126
	v_add_f32_e32 v129, v134, v127
	v_cvt_pk_bf16_f32 v186, v126, v127
	v_mfma_f32_32x32x16_bf16 v[50:65], v[122:125], v[190:193], v[50:65]
	v_exp_f32_e32 v124, v108
	v_exp_f32_e32 v125, v109
	v_add_f32_e32 v122, v128, v124
	v_add_f32_e32 v123, v129, v125
	v_cvt_pk_bf16_f32 v187, v124, v125

.LBB0_240:
	s_mov_b32 s23, s33
	s_mov_b32 s33, s31
	s_mov_b32 s31, s48
	s_mov_b32 s48, s23
	s_mov_b32 s49, s23
	s_addk_i32 s21, 0x80
	s_add_i32 s23, s22, -3
	v_lshl_add_u64 v[214:215], v[214:215], 0, s[34:35]
	s_cmp_ge_u32 s23, s16
	v_lshl_add_u64 v[216:217], v[216:217], 0, s[24:25]
	s_cbranch_scc1 .LBB0_242
	s_mov_b32 s23, s22
	s_branch .LBB0_164
.Lslow_u1e:
	s_add_i32 s22, s23, -1
	s_cmp_lt_u32 s22, s19
	s_cbranch_scc1 .Lpvo_u1e
	s_branch .Lhd_u1e
.Lslow_u1o:
	s_cmp_lt_u32 s23, s19
	s_cbranch_scc1 .Lpvo_u1o
	s_branch .Lhd_u1o

.Lotail_u1o:
	s_add_i32 s26, s23, -1
	s_cmp_lt_u32 s26, s16
	s_cbranch_scc1 .Low2_u1o
	s_waitcnt vmcnt(0)
	s_branch .LBB0_208

.LBB0_267:
	s_add_i32 s21, s22, -1
	s_cmp_lt_u32 s21, s17
	s_cselect_b64 s[44:45], -1, 0
	s_waitcnt vmcnt(2)
.LBB0_271:
	s_lshl_b32 s101, s31, 14
	v_add_u32_e32 v82, s101, v239
	v_add_u32_e32 v102, s101, v240
	ds_read_b128 v[98:101], v82
	ds_read_b128 v[114:117], v82 offset:8192
	ds_read_b128 v[118:121], v102
	s_barrier
.LBB0_277:
	s_lshl_b32 s21, s33, 14
	s_add_i32 s36, s21, 0
	s_cmp_ge_u32 s22, s19
	v_add_u32_e32 v212, s36, v245
	v_add_u32_e32 v0, s36, v246
	s_cbranch_scc1 .Lslow_u2e

.LBB0_291:
	v_mfma_f32_32x32x16_bf16 v[50:65], v[126:129], v[162:165], v[50:65]
	ds_read_b128 v[126:129], v0 offset:49152
	s_nop 1
	v_exp_f32_e32 v130, v82
	v_exp_f32_e32 v131, v83
	v_add_f32_e32 v132, v1, v130
	v_add_f32_e32 v133, v1, v131
	v_cvt_pk_bf16_f32 v166, v130, v131
	s_waitcnt lgkmcnt(3)
	v_mfma_f32_32x32x16_bf16 v[34:49], v[122:125], v[162:165], v[34:49]
	ds_read_b128 v[122:125], v0 offset:53248
	v_exp_f32_e32 v134, v84
	v_exp_f32_e32 v135, v85
	s_add_i32 s21, s22, 2
	v_add_f32_e32 v130, v132, v134
	v_add_f32_e32 v131, v133, v135
	v_cvt_pk_bf16_f32 v167, v134, v135
	s_mov_b32 m0, s100
	s_cmp_ge_u32 s21, s18
	s_cbranch_scc1 .LBB0_293
	global_load_lds_dwordx4 v214, s[80:81]
	s_add_i32 m0, s100, 0x2000
	s_nop 0
	global_load_lds_dwordx4 v214, s[62:63]
.LBB0_293:
	s_waitcnt lgkmcnt(2)
	v_mfma_f32_32x32x16_bf16 v[18:33], v[118:121], v[162:165], v[18:33]
	ds_read_b128 v[118:121], v0 offset:57344
	v_exp_f32_e32 v132, v86
	v_exp_f32_e32 v133, v87
	v_add_f32_e32 v130, v130, v132
	v_add_f32_e32 v131, v131, v133
	v_cvt_pk_bf16_f32 v168, v132, v133
	v_mfma_f32_32x32x16_bf16 v[2:17], v[114:117], v[162:165], v[2:17]
	ds_read_b128 v[114:117], v0 offset:61440
	v_exp_f32_e32 v0, v88
	v_exp_f32_e32 v132, v89
	v_add_f32_e32 v130, v130, v0
	v_add_f32_e32 v131, v131, v132
	v_cvt_pk_bf16_f32 v169, v0, v132
	s_waitcnt lgkmcnt(2)
	v_mfma_f32_32x32x16_bf16 v[50:65], v[126:129], v[170:173], v[50:65]
	v_add_u32_e32 v0, s36, v247
	ds_read_b128 v[126:129], v0 offset:49152
	v_exp_f32_e32 v132, v90
	v_exp_f32_e32 v133, v91
	v_add_f32_e32 v130, v130, v132
	v_add_f32_e32 v131, v131, v133
	v_cvt_pk_bf16_f32 v174, v132, v133
	v_mfma_f32_32x32x16_bf16 v[34:49], v[122:125], v[170:173], v[34:49]
	ds_read_b128 v[122:125], v0 offset:53248
	v_exp_f32_e32 v132, v92
	v_exp_f32_e32 v133, v93
	v_add_f32_e32 v130, v130, v132
	v_add_f32_e32 v131, v131, v133
	v_cvt_pk_bf16_f32 v175, v132, v133
.LBB0_295:
	s_waitcnt lgkmcnt(2)
	v_mfma_f32_32x32x16_bf16 v[18:33], v[118:121], v[170:173], v[18:33]
	ds_read_b128 v[118:121], v0 offset:57344
	v_exp_f32_e32 v132, v94
	v_exp_f32_e32 v133, v95
	v_add_f32_e32 v130, v130, v132
	v_add_f32_e32 v131, v131, v133
	v_cvt_pk_bf16_f32 v176, v132, v133
	v_mfma_f32_32x32x16_bf16 v[2:17], v[114:117], v[170:173], v[2:17]
	ds_read_b128 v[114:117], v0 offset:61440
	v_exp_f32_e32 v0, v96
	v_exp_f32_e32 v132, v97
	v_add_f32_e32 v130, v130, v0
	v_add_f32_e32 v131, v131, v132
	v_cvt_pk_bf16_f32 v177, v0, v132
	s_waitcnt lgkmcnt(2)
	v_mfma_f32_32x32x16_bf16 v[50:65], v[126:129], v[178:181], v[50:65]
	v_add_u32_e32 v0, s36, v248
	ds_read_b128 v[126:129], v0 offset:49152
	v_exp_f32_e32 v132, v98
	v_exp_f32_e32 v133, v99
	v_add_f32_e32 v130, v130, v132
	v_add_f32_e32 v131, v131, v133
	v_cvt_pk_bf16_f32 v182, v132, v133
	v_mfma_f32_32x32x16_bf16 v[34:49], v[122:125], v[178:181], v[34:49]
	v_exp_f32_e32 v132, v100
	v_exp_f32_e32 v133, v101
	ds_read_b128 v[122:125], v0 offset:53248
	v_add_f32_e32 v130, v130, v132
	v_add_f32_e32 v131, v131, v133
	v_cvt_pk_bf16_f32 v183, v132, v133
	s_add_i32 m0, s101, 0xc000
	s_cmp_eq_u64 s[44:45], 0
	s_cbranch_scc1 .LBB0_297
	global_load_lds_dwordx4 v216, s[96:97]
	s_add_i32 m0, s101, 0xe000
	s_nop 0
	global_load_lds_dwordx4 v216, s[58:59]
.LBB0_297:
	s_waitcnt lgkmcnt(2)
	v_mfma_f32_32x32x16_bf16 v[18:33], v[118:121], v[178:181], v[18:33]
	ds_read_b128 v[118:121], v0 offset:57344
	v_exp_f32_e32 v132, v102
	v_exp_f32_e32 v133, v103
	v_add_f32_e32 v130, v130, v132
	v_add_f32_e32 v131, v131, v133
	v_cvt_pk_bf16_f32 v184, v132, v133
	v_mfma_f32_32x32x16_bf16 v[2:17], v[114:117], v[178:181], v[2:17]
	ds_read_b128 v[114:117], v0 offset:61440
	v_exp_f32_e32 v0, v104
	v_exp_f32_e32 v132, v105
	v_add_f32_e32 v130, v130, v0
	v_add_f32_e32 v131, v131, v132
	v_cvt_pk_bf16_f32 v185, v0, v132
	s_waitcnt lgkmcnt(2)
	v_mfma_f32_32x32x16_bf16 v[50:65], v[126:129], v[186:189], v[50:65]
	v_exp_f32_e32 v0, v106
	v_exp_f32_e32 v126, v107
	v_add_f32_e32 v127, v130, v0
	v_add_f32_e32 v128, v131, v126
	v_cvt_pk_bf16_f32 v190, v0, v126
	v_mfma_f32_32x32x16_bf16 v[34:49], v[122:125], v[186:189], v[34:49]
	v_exp_f32_e32 v123, v108
	v_exp_f32_e32 v124, v109
	v_add_f32_e32 v0, v127, v123
	v_add_f32_e32 v122, v128, v124
	v_cvt_pk_bf16_f32 v191, v123, v124

.LBB0_303:
	s_cmp_lt_u32 s21, s18
	s_cselect_b64 s[44:45], -1, 0
	s_cbranch_scc0 .Lotail_u2o

.LBB0_311:
	s_mov_b32 s26, s31
	s_mov_b32 s31, s23
	s_mov_b32 s23, s28
	s_mov_b32 s28, s26
	s_mov_b32 s33, s26
	s_lshl_b32 s101, s31, 14
	v_add_u32_e32 v82, s101, v239
	v_add_u32_e32 v102, s101, v240
	ds_read_b128 v[98:101], v82
	ds_read_b128 v[114:117], v82 offset:8192
	ds_read_b128 v[118:121], v102
	s_barrier

.LBB0_331:
	v_mfma_f32_32x32x16_bf16 v[50:65], v[126:129], v[166:169], v[50:65]
	ds_read_b128 v[126:129], v0 offset:49152
	s_nop 0
	v_exp_f32_e32 v130, v82
	v_exp_f32_e32 v131, v83
	v_add_f32_e32 v132, v1, v130
	v_add_f32_e32 v133, v1, v131
	v_cvt_pk_bf16_f32 v162, v130, v131
	s_waitcnt lgkmcnt(3)
	v_mfma_f32_32x32x16_bf16 v[34:49], v[122:125], v[166:169], v[34:49]
	ds_read_b128 v[122:125], v0 offset:53248
	v_exp_f32_e32 v130, v84
	v_exp_f32_e32 v131, v85
	s_add_i32 s22, s22, 3
	v_add_f32_e32 v132, v132, v130
	v_add_f32_e32 v133, v133, v131
	v_cvt_pk_bf16_f32 v163, v130, v131
	s_mov_b32 m0, s100
	s_cmp_gt_u32 s22, s17
	s_cbranch_scc1 .LBB0_333
	global_load_lds_dwordx4 v214, s[50:51]
	s_add_i32 m0, s100, 0x2000
	s_nop 0
	global_load_lds_dwordx4 v214, s[4:5]
.LBB0_333:
	s_waitcnt lgkmcnt(2)
	v_mfma_f32_32x32x16_bf16 v[18:33], v[118:121], v[166:169], v[18:33]
	ds_read_b128 v[118:121], v0 offset:57344
	v_exp_f32_e32 v134, v86
	v_exp_f32_e32 v135, v87
	v_add_f32_e32 v132, v132, v134
	v_add_f32_e32 v133, v133, v135
	v_cvt_pk_bf16_f32 v164, v134, v135
	v_mfma_f32_32x32x16_bf16 v[2:17], v[114:117], v[166:169], v[2:17]
	ds_read_b128 v[114:117], v0 offset:61440
	v_exp_f32_e32 v0, v88
	v_exp_f32_e32 v134, v89
	v_add_f32_e32 v132, v132, v0
	v_add_f32_e32 v133, v133, v134
	v_cvt_pk_bf16_f32 v165, v0, v134
	s_waitcnt lgkmcnt(2)
	v_mfma_f32_32x32x16_bf16 v[50:65], v[126:129], v[174:177], v[50:65]
	v_add_u32_e32 v0, s36, v247
	ds_read_b128 v[126:129], v0 offset:49152
	v_exp_f32_e32 v134, v90
	v_exp_f32_e32 v135, v91
	v_add_f32_e32 v132, v132, v134
	v_add_f32_e32 v133, v133, v135
	v_cvt_pk_bf16_f32 v170, v134, v135
	v_mfma_f32_32x32x16_bf16 v[34:49], v[122:125], v[174:177], v[34:49]
	ds_read_b128 v[122:125], v0 offset:53248
	v_exp_f32_e32 v134, v92
	v_exp_f32_e32 v135, v93
	v_add_f32_e32 v132, v132, v134
	v_add_f32_e32 v133, v133, v135
	v_cvt_pk_bf16_f32 v171, v134, v135
.LBB0_335:
	s_waitcnt lgkmcnt(2)
	v_mfma_f32_32x32x16_bf16 v[18:33], v[118:121], v[174:177], v[18:33]
	ds_read_b128 v[118:121], v0 offset:57344
	v_exp_f32_e32 v130, v94
	v_exp_f32_e32 v131, v95
	v_add_f32_e32 v132, v132, v130
	v_add_f32_e32 v133, v133, v131
	v_cvt_pk_bf16_f32 v172, v130, v131
	v_mfma_f32_32x32x16_bf16 v[2:17], v[114:117], v[174:177], v[2:17]
	ds_read_b128 v[114:117], v0 offset:61440
	v_exp_f32_e32 v0, v96
	v_exp_f32_e32 v130, v97
	v_add_f32_e32 v131, v132, v0
	v_add_f32_e32 v132, v133, v130
	v_cvt_pk_bf16_f32 v173, v0, v130
	s_waitcnt lgkmcnt(2)
	v_mfma_f32_32x32x16_bf16 v[50:65], v[126:129], v[182:185], v[50:65]
	v_add_u32_e32 v0, s36, v248
	ds_read_b128 v[126:129], v0 offset:49152
	v_exp_f32_e32 v130, v98
	v_exp_f32_e32 v133, v99
	v_add_f32_e32 v131, v131, v130
	v_add_f32_e32 v134, v132, v133
	v_cvt_pk_bf16_f32 v178, v130, v133
	v_mfma_f32_32x32x16_bf16 v[34:49], v[122:125], v[182:185], v[34:49]
	v_exp_f32_e32 v130, v100
	v_exp_f32_e32 v135, v101
	ds_read_b128 v[122:125], v0 offset:53248
	v_add_f32_e32 v132, v131, v130
	v_add_f32_e32 v133, v134, v135
	v_cvt_pk_bf16_f32 v179, v130, v135
	s_add_i32 m0, s101, 0xc000
	s_cmp_eq_u64 s[44:45], 0
	s_cbranch_scc1 .LBB0_337
	global_load_lds_dwordx4 v216, s[0:1]
	s_add_i32 m0, s101, 0xe000
	s_nop 0
	global_load_lds_dwordx4 v216, s[52:53]
.LBB0_337:
	s_waitcnt lgkmcnt(2)
	v_mfma_f32_32x32x16_bf16 v[18:33], v[118:121], v[182:185], v[18:33]
	ds_read_b128 v[118:121], v0 offset:57344
	v_exp_f32_e32 v134, v102
	v_exp_f32_e32 v135, v103
	v_add_f32_e32 v132, v132, v134
	v_add_f32_e32 v133, v133, v135
	v_cvt_pk_bf16_f32 v180, v134, v135
	v_mfma_f32_32x32x16_bf16 v[2:17], v[114:117], v[182:185], v[2:17]
	ds_read_b128 v[114:117], v0 offset:61440
	v_exp_f32_e32 v0, v104
	v_exp_f32_e32 v134, v105
	v_add_f32_e32 v132, v132, v0
	v_add_f32_e32 v133, v133, v134
	v_cvt_pk_bf16_f32 v181, v0, v134
	s_waitcnt lgkmcnt(2)
	v_mfma_f32_32x32x16_bf16 v[50:65], v[126:129], v[190:193], v[50:65]
	v_exp_f32_e32 v0, v106
	v_exp_f32_e32 v126, v107
	v_add_f32_e32 v127, v132, v0
	v_add_f32_e32 v128, v133, v126
	v_cvt_pk_bf16_f32 v186, v0, v126
	v_mfma_f32_32x32x16_bf16 v[34:49], v[122:125], v[190:193], v[34:49]
	v_exp_f32_e32 v123, v108
	v_exp_f32_e32 v124, v109
	v_add_f32_e32 v0, v127, v123
	v_add_f32_e32 v122, v128, v124
	v_cvt_pk_bf16_f32 v187, v123, v124

.LBB0_343:
	s_mov_b32 s22, s31
	s_mov_b32 s31, s23
	s_mov_b32 s23, s28
	s_mov_b32 s28, s22
	s_mov_b32 s33, s22
	s_addk_i32 s20, 0x80
	s_add_i32 s22, s21, -3
	v_lshl_add_u64 v[214:215], v[214:215], 0, s[34:35]
	s_cmp_ge_u32 s22, s17
	v_lshl_add_u64 v[216:217], v[216:217], 0, s[24:25]
	s_cbranch_scc1 .LBB0_345
	s_mov_b32 s22, s21
	s_branch .LBB0_267
.Lslow_u2e:
	s_add_i32 s21, s22, -1
	s_cmp_lt_u32 s21, s19
	s_cbranch_scc1 .Lpvo_u2e
	s_branch .Lhd_u2e
.Lslow_u2o:
	s_cmp_lt_u32 s22, s19
	s_cbranch_scc1 .Lpvo_u2o
	s_branch .Lhd_u2o

.Lotail_u2o:
	s_add_i32 s26, s22, -1
	s_cmp_lt_u32 s26, s17
	s_cbranch_scc1 .Low2_u2o
	s_waitcnt vmcnt(0)
	s_branch .LBB0_311
